# v050 g3 converters 18 items per wave (no layer-0 gate/up left in the prologue)
# baseline (speedup 1.0000x reference)
; DEV void phase_prologue_a(const Frame& F0) {
;     ...
;         constexpr int GU_NB = 2 * FF / 32, GU_ITEMS = 16 * GU_NB;
;         for (int it = F.gw; it < NE * GU_ITEMS; it += F.NGW) { const int e = it / GU_ITEMS, r = it % GU_ITEMS, kb = r / GU_NB, nb = r % GU_NB; const int d0 = 32 * nb, j = d0 >> 8, w = d0 & 255;
;             const float* src = (w < 128 ? GIN(I_WGATE) : GIN(I_WUP)) + ((size_t)l * NE + e) * 1024 * FF;
;             tr_item(src, FF, 128 * j + (w & 127), 64 * kb, (bf16_t*)(F.ws + WS_WGU) + ((size_t)l * NE + e) * 2 * FF * 1024, 1024, d0, scr, F.lane); }
.LBB0_24:
	s_andn2_b64 vcc, exec, s[10:11]
	s_cbranch_vccnz .LBB0_29
	s_lshl_b64 s[20:21], s[2:3], 27
	s_mov_b32 s28, s31
	v_readlane_b32 s100, v255, 51
	s_cmp_lg_u32 s100, 0x100
	s_cbranch_scc1 .Lpro_gu_all
	s_cmp_lg_u32 s14, 0
	s_cbranch_scc1 .LBB0_29
	s_branch .LBB0_29

; #define WAIT_VM(n) do {} while (0)
; #define LAUNDER_S(x) do {} while (0)
; #define WAIT_VM(n) asm volatile("s_waitcnt vmcnt(" #n ")" ::: "memory")
; #define LAUNDER_S(x) asm volatile("" : "+s"(x))
; DEV int lane_id() { return (int)__builtin_amdgcn_mbcnt_hi(~0u, __builtin_amdgcn_mbcnt_lo(~0u, 0u)); }
; DEV void xcd_barrier(const XcdBarrier& b) {
;     WAIT_VM(0);
;     __syncthreads();
;     int bw = b.wave; LAUNDER_S(bw);
;     if (bw == 0 && lane_id() == 0) {
; DEV void phase_prologue_a(const Frame& F0) {
;     ...
;         constexpr int GU_NB = 2 * FF / 32, GU_ITEMS = 16 * GU_NB;
;         for (int it = F.gw; it < NE * GU_ITEMS; it += F.NGW) { const int e = it / GU_ITEMS, r = it % GU_ITEMS, kb = r / GU_NB, nb = r % GU_NB; const int d0 = 32 * nb, j = d0 >> 8, w = d0 & 255;
.LBB0_115:
	s_or_b64 exec, exec, s[30:31]
	s_cselect_b32 s38, 1, 0
	v_writelane_b32 v255, s38, 61
	v_readlane_b32 s38, v255, 59
	s_add_i32 s39, s38, 1
	v_writelane_b32 v255, s39, 59
	s_mov_b32 s41, 0
	v_readlane_b32 s39, v251, 29
	s_cmp_eq_u32 s39, 0
	s_cbranch_scc1 .Lbw0_none
	v_readlane_b32 s40, v255, 51
	s_cmp_lg_u32 s40, 0x100
	s_cbranch_scc1 .Lbw0_none
	v_readlane_b32 s40, v255, 48
	s_mul_i32 s40, s40, 7
	s_mul_i32 s38, s38, 0x700
	s_add_i32 s40, s40, s38
	s_add_i32 s40, s40, s39
	s_add_i32 s40, s40, -1
	s_cmp_lt_u32 s40, 0xf880
	s_cbranch_scc0 .Lbw0_none
	s_mov_b32 s41, 0
	s_add_i32 s40, s40, 0x4380
	s_cmp_lt_u32 s40, 0x8000
	s_cbranch_scc1 .Lbw0_have
	s_mov_b32 s41, 1
	s_sub_i32 s40, s40, 0x8000
	s_cmp_lt_u32 s40, 0x3c80
	s_cbranch_scc1 .Lbw0_have
	s_mov_b32 s41, 2
	s_sub_i32 s40, s40, 0x3c80
	s_cmp_lt_u32 s40, 0x3280
	s_cbranch_scc1 .Lbw0_have
	s_mov_b32 s41, 3
	s_sub_i32 s40, s40, 0x3280

; #define WAIT_VM(n) do {} while (0)
; #define LAUNDER_S(x) do {} while (0)
; #define WAIT_VM(n) asm volatile("s_waitcnt vmcnt(" #n ")" ::: "memory")
; #define LAUNDER_S(x) asm volatile("" : "+s"(x))
; DEV int lane_id() { return (int)__builtin_amdgcn_mbcnt_hi(~0u, __builtin_amdgcn_mbcnt_lo(~0u, 0u)); }
; DEV void xcd_barrier(const XcdBarrier& b) {
;     WAIT_VM(0);
;     __syncthreads();
;     int bw = b.wave; LAUNDER_S(bw);
;     if (bw == 0 && lane_id() == 0) {
; DEV void phase_prologue_a(const Frame& F0) {
;     ...
;         constexpr int GU_NB = 2 * FF / 32, GU_ITEMS = 16 * GU_NB;
;         for (int it = F.gw; it < NE * GU_ITEMS; it += F.NGW) { const int e = it / GU_ITEMS, r = it % GU_ITEMS, kb = r / GU_NB, nb = r % GU_NB; const int d0 = 32 * nb, j = d0 >> 8, w = d0 & 255;
.LBB0_241:
	v_writelane_b32 v253, s58, 51
	s_nop 1
	v_writelane_b32 v253, s59, 52
	v_writelane_b32 v253, s56, 53
	s_nop 1
	v_writelane_b32 v253, s57, 54
	s_or_b64 exec, exec, s[34:35]
	s_cselect_b32 s38, 1, 0
	v_writelane_b32 v255, s38, 61
	v_readlane_b32 s38, v255, 59
	s_add_i32 s39, s38, 1
	v_writelane_b32 v255, s39, 59
	s_mov_b32 s41, 0
	v_readlane_b32 s39, v251, 29
	s_cmp_eq_u32 s39, 0
	s_cbranch_scc1 .Lbw2_none
	v_readlane_b32 s40, v255, 51
	s_cmp_lg_u32 s40, 0x100
	s_cbranch_scc1 .Lbw2_none
	v_readlane_b32 s40, v255, 48
	s_mul_i32 s40, s40, 7
	s_mul_i32 s38, s38, 0x700
	s_add_i32 s40, s40, s38
	s_add_i32 s40, s40, s39
	s_add_i32 s40, s40, -1
	s_cmp_lt_u32 s40, 0xf880
	s_cbranch_scc0 .Lbw2_none
	s_mov_b32 s41, 0
	s_add_i32 s40, s40, 0x4380
	s_cmp_lt_u32 s40, 0x8000
	s_cbranch_scc1 .Lbw2_have
	s_mov_b32 s41, 1
	s_sub_i32 s40, s40, 0x8000
	s_cmp_lt_u32 s40, 0x3c80
	s_cbranch_scc1 .Lbw2_have
	s_mov_b32 s41, 2
	s_sub_i32 s40, s40, 0x3c80
	s_cmp_lt_u32 s40, 0x3280
	s_cbranch_scc1 .Lbw2_have
	s_mov_b32 s41, 3
	s_sub_i32 s40, s40, 0x3280

; #define WAIT_VM(n) do {} while (0)
; #define LAUNDER_S(x) do {} while (0)
; #define WAIT_VM(n) asm volatile("s_waitcnt vmcnt(" #n ")" ::: "memory")
; #define LAUNDER_S(x) asm volatile("" : "+s"(x))
; DEV int lane_id() { return (int)__builtin_amdgcn_mbcnt_hi(~0u, __builtin_amdgcn_mbcnt_lo(~0u, 0u)); }
; DEV void xcd_barrier(const XcdBarrier& b) {
;     WAIT_VM(0);
;     __syncthreads();
;     int bw = b.wave; LAUNDER_S(bw);
;     if (bw == 0 && lane_id() == 0) {
; DEV void phase_prologue_a(const Frame& F0) {
;     ...
;         constexpr int GU_NB = 2 * FF / 32, GU_ITEMS = 16 * GU_NB;
;         for (int it = F.gw; it < NE * GU_ITEMS; it += F.NGW) { const int e = it / GU_ITEMS, r = it % GU_ITEMS, kb = r / GU_NB, nb = r % GU_NB; const int d0 = 32 * nb, j = d0 >> 8, w = d0 & 255;
.LBB0_422:
	s_or_b64 exec, exec, s[34:35]
	s_cselect_b32 s38, 1, 0
	v_writelane_b32 v255, s38, 61
	v_readlane_b32 s38, v255, 59
	s_add_i32 s39, s38, 1
	v_writelane_b32 v255, s39, 59
	s_mov_b32 s41, 0
	v_readlane_b32 s39, v251, 29
	s_cmp_eq_u32 s39, 0
	s_cbranch_scc1 .Lbw3_none
	v_readlane_b32 s40, v255, 51
	s_cmp_lg_u32 s40, 0x100
	s_cbranch_scc1 .Lbw3_none
	v_readlane_b32 s40, v255, 48
	s_mul_i32 s40, s40, 7
	s_mul_i32 s38, s38, 0x700
	s_add_i32 s40, s40, s38
	s_add_i32 s40, s40, s39
	s_add_i32 s40, s40, -1
	s_cmp_lt_u32 s40, 0xf880
	s_cbranch_scc0 .Lbw3_none
	s_mov_b32 s41, 0
	s_add_i32 s40, s40, 0x4380
	s_cmp_lt_u32 s40, 0x8000
	s_cbranch_scc1 .Lbw3_have
	s_mov_b32 s41, 1
	s_sub_i32 s40, s40, 0x8000
	s_cmp_lt_u32 s40, 0x3c80
	s_cbranch_scc1 .Lbw3_have
	s_mov_b32 s41, 2
	s_sub_i32 s40, s40, 0x3c80
	s_cmp_lt_u32 s40, 0x3280
	s_cbranch_scc1 .Lbw3_have
	s_mov_b32 s41, 3
	s_sub_i32 s40, s40, 0x3280

; #define WAIT_VM(n) do {} while (0)
; #define LAUNDER_S(x) do {} while (0)
; #define WAIT_VM(n) asm volatile("s_waitcnt vmcnt(" #n ")" ::: "memory")
; #define LAUNDER_S(x) asm volatile("" : "+s"(x))
; DEV int lane_id() { return (int)__builtin_amdgcn_mbcnt_hi(~0u, __builtin_amdgcn_mbcnt_lo(~0u, 0u)); }
; DEV void xcd_barrier(const XcdBarrier& b) {
;     WAIT_VM(0);
;     __syncthreads();
;     int bw = b.wave; LAUNDER_S(bw);
;     if (bw == 0 && lane_id() == 0) {
; DEV void phase_prologue_a(const Frame& F0) {
;     ...
;         constexpr int GU_NB = 2 * FF / 32, GU_ITEMS = 16 * GU_NB;
;         for (int it = F.gw; it < NE * GU_ITEMS; it += F.NGW) { const int e = it / GU_ITEMS, r = it % GU_ITEMS, kb = r / GU_NB, nb = r % GU_NB; const int d0 = 32 * nb, j = d0 >> 8, w = d0 & 255;
.Lxb4_join:
.LBB0_811:
	s_or_b64 exec, exec, s[34:35]
	s_cselect_b32 s38, 1, 0
	v_writelane_b32 v255, s38, 61
	v_readlane_b32 s38, v255, 59
	s_add_i32 s39, s38, 1
	v_writelane_b32 v255, s39, 59
	s_mov_b32 s41, 0
	v_readlane_b32 s39, v251, 29
	s_cmp_eq_u32 s39, 0
	s_cbranch_scc1 .Lbw4_none
	v_readlane_b32 s40, v255, 51
	s_cmp_lg_u32 s40, 0x100
	s_cbranch_scc1 .Lbw4_none
	v_readlane_b32 s40, v255, 48
	s_mul_i32 s40, s40, 7
	s_mul_i32 s38, s38, 0x700
	s_add_i32 s40, s40, s38
	s_add_i32 s40, s40, s39
	s_add_i32 s40, s40, -1
	s_cmp_lt_u32 s40, 0xf880
	s_cbranch_scc0 .Lbw4_none
	s_mov_b32 s41, 0
	s_add_i32 s40, s40, 0x4380
	s_cmp_lt_u32 s40, 0x8000
	s_cbranch_scc1 .Lbw4_have
	s_mov_b32 s41, 1
	s_sub_i32 s40, s40, 0x8000
	s_cmp_lt_u32 s40, 0x3c80
	s_cbranch_scc1 .Lbw4_have
	s_mov_b32 s41, 2
	s_sub_i32 s40, s40, 0x3c80
	s_cmp_lt_u32 s40, 0x3280
	s_cbranch_scc1 .Lbw4_have
	s_mov_b32 s41, 3
	s_sub_i32 s40, s40, 0x3280

; #define WAVE_LDS_SYNC() do { int _z = 0; (void)emu::wave_xchg(&_z, 4); } while (0)
; #define LAS __attribute__((address_space(3)))
; #define WAVE_LDS_SYNC() asm volatile("s_waitcnt lgkmcnt(0)" ::: "memory")
; #define NT_LOAD(p) __builtin_nontemporal_load(p)
; DEV void tr_item(const float* W, int ldw, int col0, int k0, bf16_t* WT, int K, int row0, LAS float* scr, int lane) {
;     ...
;     for (int i = 0; i < 32; ++i) { const int kk = 2 * i + (lane >> 5); scr[kk * 33 + (lane & 31)] = NT_LOAD(&W[(size_t)(k0 + kk) * ldw + col0 + (lane & 31)]); }
;     WAVE_LDS_SYNC();
;     const int c = lane & 7;
; #pragma unroll
;     for (int j = 0; j < 4; ++j) { const int n = (lane >> 3) + 8 * j; const LAS float* s = scr + (8 * c) * 33 + n;
; DEV void phase_prologue_a(const Frame& F0) {
;     ...
;         constexpr int GU_NB = 2 * FF / 32, GU_ITEMS = 16 * GU_NB;
;         for (int it = F.gw; it < NE * GU_ITEMS; it += F.NGW) { const int e = it / GU_ITEMS, r = it % GU_ITEMS, kb = r / GU_NB, nb = r % GU_NB; const int d0 = 32 * nb, j = d0 >> 8, w = d0 & 255;
;             const float* src = (w < 128 ? GIN(I_WGATE) : GIN(I_WUP)) + ((size_t)l * NE + e) * 1024 * FF;
;             tr_item(src, FF, 128 * j + (w & 127), 64 * kb, (bf16_t*)(F.ws + WS_WGU) + ((size_t)l * NE + e) * 2 * FF * 1024, 1024, d0, scr, F.lane); }
.Lsg_entry:
	v_readlane_b32 s36, v253, 62
	s_cmp_gt_u32 s36, 2
	s_cbranch_scc1 .Lsg_done
	v_readlane_b32 s2, v255, 51
	s_cmp_lg_u32 s2, 0x100
	s_cbranch_scc1 .Lsg_done
	v_readlane_b32 s2, v255, 48
	s_cmp_lt_u32 s2, 0x88
	s_cbranch_scc1 .Lsg_done
	v_readlane_b32 s3, v251, 29
	s_sub_i32 s2, s2, 0x88
	s_lshl_b32 s2, s2, 3
	s_add_i32 s2, s2, s3
	v_readlane_b32 s6, v255, 53
	v_readlane_b32 s7, v255, 54
	v_readlane_b32 s4, v255, 55
	v_readlane_b32 s5, v255, 56
	v_readlane_b32 s34, v255, 57
	v_readlane_b32 s35, v255, 58
	s_add_u32 s6, s6, 0x2bc8000
	s_addc_u32 s7, s7, 0
	s_mov_b32 s8, 0
	s_mov_b32 s37, 0
	s_cmp_eq_u32 s36, 0
	s_cbranch_scc1 .Lsg_go
	s_mov_b32 s8, 0x8000000
	s_mov_b32 s37, 0x3c80
	s_cmp_eq_u32 s36, 1
	s_cbranch_scc1 .Lsg_go
	s_mov_b32 s8, 0x10000000
	s_mov_b32 s37, 0x3280
.Lsg_go:
	s_add_u32 s4, s4, s8
	s_addc_u32 s5, s5, 0
	s_add_u32 s34, s34, s8
	s_addc_u32 s35, s35, 0
	s_add_u32 s6, s6, s8
	s_addc_u32 s7, s7, 0
	s_add_i32 s2, s2, s37
	s_add_i32 s101, s37, 0x4380
	s_lshl_b32 s30, s3, 14
	v_and_b32_e32 v120, 31, v200
	v_lshlrev_b32_e32 v2, 2, v120
	v_lshrrev_b32_e32 v3, 5, v200
	v_and_b32_e32 v4, 7, v200
	v_lshrrev_b32_e32 v6, 3, v200
	v_mul_u32_u24_e32 v7, 33, v3
	v_add_u32_e32 v7, v7, v120
	v_lshl_add_u32 v7, v7, 2, s30
	v_add_u32_e32 v8, 0x400, v7
	v_add_u32_e32 v9, 0x840, v7
	v_add_u32_e32 v10, 0xc40, v7
	v_add_u32_e32 v11, 0x1080, v7
	v_add_u32_e32 v12, 0x1480, v7
	v_add_u32_e32 v13, 0x18c0, v7
	v_add_u32_e32 v14, 0x1cc0, v7
	v_mul_u32_u24_e32 v120, 0x108, v4
	v_add_u32_e32 v120, v120, v6
	v_lshl_add_u32 v15, v120, 2, s30
	v_lshl_add_u32 v122, v3, 13, v2
	v_mov_b32_e32 v123, 0
	v_lshlrev_b32_e32 v124, 4, v4
	v_lshl_add_u32 v124, v6, 11, v124
	v_mov_b32_e32 v125, 0
	s_mov_b64 s[40:41], 0x20000
	s_mov_b64 s[42:43], 0x4000
	s_mov_b64 s[44:45], 0x4000
